# phase 12 tile start de-serialised: the 4 gathered-row list entries of a tile loaded together with one wait (was 4 load+wait pairs)
# baseline (speedup 1.0000x reference)
.LBB0_908:
	global_load_dwordx4 v[16:19], v65, s[64:65]
	global_load_dwordx4 v[8:11], v65, s[64:65] offset:16
	global_load_dwordx4 v[4:7], v65, s[64:65] offset:32
	global_load_dwordx4 v[0:3], v65, s[64:65] offset:48
	s_ashr_i32 s36, s40, 3
	s_cmp_gt_i32 s36, -1
	s_cselect_b64 s[0:1], -1, 0
	global_load_dwordx4 v[12:15], v65, s[68:69] offset:16
	global_load_dwordx4 v[20:23], v65, s[68:69]
	s_waitcnt vmcnt(5)
	v_readfirstlane_b32 s14, v17
	v_readfirstlane_b32 s8, v16
	s_add_i32 s6, s8, 0x7f
	s_add_i32 s7, s14, 0x7f
	s_ashr_i32 s9, s7, 7
	s_ashr_i32 s10, s6, 7
	s_cmp_lt_i32 s36, s10
	s_cselect_b64 s[6:7], -1, 0
	s_and_b64 s[0:1], s[0:1], s[6:7]
	s_and_b64 s[0:1], s[0:1], exec
	s_cselect_b32 s15, s36, 0
	s_cselect_b32 s16, s8, 0
	s_cmp_ge_i32 s36, s10
	s_cselect_b64 s[6:7], -1, 0
	s_add_i32 s18, s9, s10
	s_cmp_lt_i32 s36, s18
	s_cselect_b64 s[8:9], -1, 0
	v_add_u32_e32 v16, 0x7f, v18
	s_sub_i32 s17, s36, s10
	s_and_b64 s[10:11], s[6:7], s[8:9]
	v_ashrrev_i32_e32 v16, 7, v16
	v_cndmask_b32_e64 v29, 0, 1, s[10:11]
	s_and_b64 s[10:11], s[10:11], exec
	v_add_u32_e32 v17, 0x7f, v19
	v_add_u32_e32 v16, s18, v16
	s_cselect_b32 s37, s17, s15
	s_cselect_b32 s19, s14, s16
	s_cmp_ge_i32 s36, s18
	s_waitcnt vmcnt(4)
	v_add_u32_e32 v24, 0x7f, v8
	v_ashrrev_i32_e32 v17, 7, v17
	v_cmp_lt_i32_e32 vcc, s36, v16
	s_cselect_b64 s[22:23], -1, 0
	v_add_u32_e32 v25, 0x7f, v9
	v_ashrrev_i32_e32 v24, 7, v24
	v_add_u32_e32 v17, v17, v16
	s_sub_i32 s41, s36, s18
	s_and_b64 vcc, s[22:23], vcc
	v_add_u32_e32 v26, 0x7f, v10
	v_ashrrev_i32_e32 v25, 7, v25
	v_cmp_ge_i32_e64 s[0:1], s36, v16
	v_cmp_lt_i32_e64 s[6:7], s36, v17
	v_add_u32_e32 v24, v24, v17
	v_mov_b32_e32 v30, s19
	s_and_b64 s[42:43], vcc, exec
	v_add_u32_e32 v27, 0x7f, v11
	v_ashrrev_i32_e32 v26, 7, v26
	v_cmp_ge_i32_e64 s[8:9], s36, v17
	v_cmp_lt_i32_e64 s[10:11], s36, v24
	v_add_u32_e32 v25, v25, v24
	v_cndmask_b32_e32 v18, v30, v18, vcc
	s_cselect_b32 s37, s41, s37
	s_and_b64 s[0:1], s[0:1], s[6:7]
	s_waitcnt vmcnt(3)
	v_add_u32_e32 v28, 0x7f, v4
	v_ashrrev_i32_e32 v27, 7, v27
	v_sub_u32_e32 v16, s36, v16
	v_cmp_ge_i32_e64 s[12:13], s36, v24
	v_cmp_lt_i32_e64 s[14:15], s36, v25
	v_add_u32_e32 v26, v26, v25
	v_cndmask_b32_e64 v29, v29, 2, vcc
	v_mov_b32_e32 v30, s37
	v_cndmask_b32_e64 v18, v18, v19, s[0:1]
	s_and_b64 s[6:7], s[8:9], s[10:11]
	v_ashrrev_i32_e32 v28, 7, v28
	v_sub_u32_e32 v17, s36, v17
	v_cmp_ge_i32_e64 s[16:17], s36, v25
	v_cmp_lt_i32_e64 s[18:19], s36, v26
	v_add_u32_e32 v27, v27, v26
	v_cndmask_b32_e64 v29, v29, 3, s[0:1]
	v_cndmask_b32_e64 v16, v30, v16, s[0:1]
	v_cndmask_b32_e64 v8, v18, v8, s[6:7]
	s_and_b64 s[0:1], s[12:13], s[14:15]
	v_sub_u32_e32 v24, s36, v24
	v_cmp_ge_i32_e64 s[20:21], s36, v26
	v_cmp_lt_i32_e64 s[22:23], s36, v27
	v_add_u32_e32 v28, v28, v27
	v_cndmask_b32_e64 v19, v29, 4, s[6:7]
	v_cndmask_b32_e64 v16, v16, v17, s[6:7]
	v_cndmask_b32_e64 v8, v8, v9, s[0:1]
	s_and_b64 s[6:7], s[16:17], s[18:19]
	v_cmp_ge_i32_e64 s[24:25], s36, v27
	v_cmp_lt_i32_e32 vcc, s36, v28
	v_cndmask_b32_e64 v18, v19, 5, s[0:1]
	v_cndmask_b32_e64 v16, v16, v24, s[0:1]
	v_cndmask_b32_e64 v8, v8, v10, s[6:7]
	s_and_b64 s[0:1], s[20:21], s[22:23]
	v_cndmask_b32_e64 v8, v8, v11, s[0:1]
	s_and_b64 vcc, s[24:25], vcc
	v_sub_u32_e32 v25, s36, v25
	v_cndmask_b32_e32 v4, v8, v4, vcc
	v_add_u32_e32 v8, 0x7f, v5
	v_sub_u32_e32 v26, s36, v26
	v_cndmask_b32_e64 v9, v18, 6, s[6:7]
	v_cndmask_b32_e64 v10, v16, v25, s[6:7]
	v_ashrrev_i32_e32 v8, 7, v8
	v_sub_u32_e32 v27, s36, v27
	v_cndmask_b32_e64 v9, v9, 7, s[0:1]
	v_cndmask_b32_e64 v10, v10, v26, s[0:1]
	v_add_u32_e32 v8, v8, v28
	v_cndmask_b32_e64 v9, v9, 8, vcc
	v_cndmask_b32_e32 v10, v10, v27, vcc
	v_cmp_ge_i32_e32 vcc, s36, v28
	v_cmp_lt_i32_e64 s[0:1], s36, v8
	s_and_b64 vcc, vcc, s[0:1]
	v_cndmask_b32_e32 v4, v4, v5, vcc
	v_add_u32_e32 v5, 0x7f, v6
	v_ashrrev_i32_e32 v5, 7, v5
	v_sub_u32_e32 v11, s36, v28
	v_add_u32_e32 v5, v5, v8
	v_cndmask_b32_e64 v9, v9, 9, vcc
	v_cndmask_b32_e32 v10, v10, v11, vcc
	v_cmp_ge_i32_e32 vcc, s36, v8
	v_cmp_lt_i32_e64 s[0:1], s36, v5
	s_and_b64 vcc, vcc, s[0:1]
	v_cndmask_b32_e32 v4, v4, v6, vcc
	v_add_u32_e32 v6, 0x7f, v7
	v_ashrrev_i32_e32 v6, 7, v6
	v_sub_u32_e32 v8, s36, v8
	v_add_u32_e32 v6, v6, v5
	v_cndmask_b32_e64 v9, v9, 10, vcc
	v_cndmask_b32_e32 v8, v10, v8, vcc
	v_cmp_ge_i32_e32 vcc, s36, v5
	v_cmp_lt_i32_e64 s[0:1], s36, v6
	s_and_b64 vcc, vcc, s[0:1]
	v_cndmask_b32_e32 v4, v4, v7, vcc
	s_waitcnt vmcnt(2)
	v_add_u32_e32 v7, 0x7f, v0
	v_ashrrev_i32_e32 v7, 7, v7
	v_sub_u32_e32 v5, s36, v5
	v_add_u32_e32 v7, v7, v6
	v_cndmask_b32_e64 v9, v9, 11, vcc
	v_cndmask_b32_e32 v5, v8, v5, vcc
	v_cmp_ge_i32_e32 vcc, s36, v6
	v_cmp_lt_i32_e64 s[0:1], s36, v7
	s_and_b64 vcc, vcc, s[0:1]
	v_cndmask_b32_e32 v0, v4, v0, vcc
	v_add_u32_e32 v4, 0x7f, v1
	v_ashrrev_i32_e32 v4, 7, v4
	v_sub_u32_e32 v6, s36, v6
	v_add_u32_e32 v4, v4, v7
	v_cndmask_b32_e64 v8, v9, 12, vcc
	v_cndmask_b32_e32 v5, v5, v6, vcc
	v_cmp_ge_i32_e32 vcc, s36, v7
	v_cmp_lt_i32_e64 s[0:1], s36, v4
	s_and_b64 vcc, vcc, s[0:1]
	v_cndmask_b32_e32 v0, v0, v1, vcc
	v_add_u32_e32 v1, 0x7f, v2
	v_ashrrev_i32_e32 v1, 7, v1
	v_sub_u32_e32 v6, s36, v7
	v_add_u32_e32 v1, v1, v4
	v_cndmask_b32_e64 v7, v8, 13, vcc
	v_cndmask_b32_e32 v5, v5, v6, vcc
	v_cmp_ge_i32_e32 vcc, s36, v4
	v_cmp_lt_i32_e64 s[0:1], s36, v1
	s_and_b64 vcc, vcc, s[0:1]
	v_cndmask_b32_e32 v0, v0, v2, vcc
	v_add_u32_e32 v2, 0x7f, v3
	v_ashrrev_i32_e32 v2, 7, v2
	v_sub_u32_e32 v4, s36, v4
	v_add_u32_e32 v8, v2, v1
	v_cndmask_b32_e64 v6, v7, 14, vcc
	v_cndmask_b32_e32 v4, v5, v4, vcc
	v_cmp_ge_i32_e32 vcc, s36, v1
	v_cmp_lt_i32_e64 s[0:1], s36, v8
	v_sub_u32_e32 v1, s36, v1
	s_and_b64 vcc, vcc, s[0:1]
	v_cndmask_b32_e64 v9, v6, 15, vcc
	v_cndmask_b32_e32 v10, v4, v1, vcc
	v_cndmask_b32_e32 v11, v0, v3, vcc
	global_load_dwordx4 v[0:3], v65, s[68:69] offset:48
	global_load_dwordx4 v[4:7], v65, s[68:69] offset:32
	s_waitcnt vmcnt(2)
	v_add_u32_e32 v16, 0x7f, v20
	v_ashrrev_i32_e32 v16, 7, v16
	v_add_u32_e32 v16, v16, v8
	v_cmp_ge_i32_e32 vcc, s36, v8
	v_cmp_lt_i32_e64 s[0:1], s36, v16
	v_sub_u32_e32 v8, s36, v8
	s_and_b64 vcc, vcc, s[0:1]
	v_cndmask_b32_e32 v8, v10, v8, vcc
	v_cndmask_b32_e32 v10, v11, v20, vcc
	v_add_u32_e32 v11, 0x7f, v21
	v_ashrrev_i32_e32 v11, 7, v11
	v_add_u32_e32 v11, v11, v16
	v_cndmask_b32_e64 v9, v9, 16, vcc
	v_cmp_ge_i32_e32 vcc, s36, v16
	v_cmp_lt_i32_e64 s[0:1], s36, v11
	v_sub_u32_e32 v16, s36, v16
	s_and_b64 vcc, vcc, s[0:1]
	v_cndmask_b32_e32 v8, v8, v16, vcc
	v_add_u32_e32 v16, 0x7f, v22
	v_ashrrev_i32_e32 v16, 7, v16
	v_add_u32_e32 v16, v16, v11
	v_cndmask_b32_e64 v9, v9, 17, vcc
	v_cndmask_b32_e32 v10, v10, v21, vcc
	v_cmp_ge_i32_e32 vcc, s36, v11
	v_cmp_lt_i32_e64 s[0:1], s36, v16
	v_sub_u32_e32 v11, s36, v11
	s_and_b64 vcc, vcc, s[0:1]
	v_cndmask_b32_e32 v8, v8, v11, vcc
	v_add_u32_e32 v11, 0x7f, v23
	v_ashrrev_i32_e32 v11, 7, v11
	v_add_u32_e32 v11, v11, v16
	v_cndmask_b32_e64 v9, v9, 18, vcc
	v_cndmask_b32_e32 v10, v10, v22, vcc
	v_cmp_ge_i32_e32 vcc, s36, v16
	v_cmp_lt_i32_e64 s[0:1], s36, v11
	v_sub_u32_e32 v16, s36, v16
	s_and_b64 vcc, vcc, s[0:1]
	v_cndmask_b32_e32 v8, v8, v16, vcc
	v_add_u32_e32 v16, 0x7f, v12
	v_ashrrev_i32_e32 v16, 7, v16
	v_add_u32_e32 v16, v16, v11
	v_cndmask_b32_e64 v9, v9, 19, vcc
	v_cndmask_b32_e32 v10, v10, v23, vcc
	v_cmp_ge_i32_e32 vcc, s36, v11
	v_cmp_lt_i32_e64 s[0:1], s36, v16
	v_sub_u32_e32 v11, s36, v11
	s_and_b64 vcc, vcc, s[0:1]
	v_cndmask_b32_e32 v8, v8, v11, vcc
	v_add_u32_e32 v11, 0x7f, v13
	v_ashrrev_i32_e32 v11, 7, v11
	v_add_u32_e32 v11, v11, v16
	v_cndmask_b32_e64 v9, v9, 20, vcc
	v_cndmask_b32_e32 v10, v10, v12, vcc
	v_cmp_ge_i32_e32 vcc, s36, v16
	v_cmp_lt_i32_e64 s[0:1], s36, v11
	v_sub_u32_e32 v12, s36, v16
	s_and_b64 vcc, vcc, s[0:1]
	v_cndmask_b32_e32 v8, v8, v12, vcc
	v_add_u32_e32 v12, 0x7f, v14
	v_ashrrev_i32_e32 v12, 7, v12
	v_add_u32_e32 v12, v12, v11
	v_cndmask_b32_e64 v9, v9, 21, vcc
	v_cndmask_b32_e32 v10, v10, v13, vcc
	v_cmp_ge_i32_e32 vcc, s36, v11
	v_cmp_lt_i32_e64 s[0:1], s36, v12
	v_sub_u32_e32 v11, s36, v11
	s_and_b64 vcc, vcc, s[0:1]
	v_cndmask_b32_e32 v8, v8, v11, vcc
	v_add_u32_e32 v11, 0x7f, v15
	v_ashrrev_i32_e32 v11, 7, v11
	v_add_u32_e32 v11, v11, v12
	v_cndmask_b32_e64 v9, v9, 22, vcc
	v_cndmask_b32_e32 v10, v10, v14, vcc
	v_cmp_ge_i32_e32 vcc, s36, v12
	v_cmp_lt_i32_e64 s[0:1], s36, v11
	v_sub_u32_e32 v12, s36, v12
	s_and_b64 vcc, vcc, s[0:1]
	v_cndmask_b32_e32 v8, v8, v12, vcc
	v_cndmask_b32_e64 v9, v9, 23, vcc
	s_waitcnt vmcnt(0)
	v_add_u32_e32 v12, 0x7f, v4
	v_ashrrev_i32_e32 v12, 7, v12
	v_add_u32_e32 v12, v12, v11
	v_cndmask_b32_e32 v10, v10, v15, vcc
	v_cmp_ge_i32_e32 vcc, s36, v11
	v_cmp_lt_i32_e64 s[0:1], s36, v12
	s_and_b64 vcc, vcc, s[0:1]
	v_cndmask_b32_e32 v4, v10, v4, vcc
	v_add_u32_e32 v10, 0x7f, v5
	v_ashrrev_i32_e32 v10, 7, v10
	v_sub_u32_e32 v11, s36, v11
	v_add_u32_e32 v10, v10, v12
	v_cndmask_b32_e64 v9, v9, 24, vcc
	v_cndmask_b32_e32 v8, v8, v11, vcc
	v_cmp_ge_i32_e32 vcc, s36, v12
	v_cmp_lt_i32_e64 s[0:1], s36, v10
	s_and_b64 vcc, vcc, s[0:1]
	v_cndmask_b32_e32 v4, v4, v5, vcc
	v_add_u32_e32 v5, 0x7f, v6
	v_ashrrev_i32_e32 v5, 7, v5
	v_sub_u32_e32 v11, s36, v12
	v_add_u32_e32 v5, v5, v10
	v_cndmask_b32_e64 v9, v9, 25, vcc
	v_cndmask_b32_e32 v8, v8, v11, vcc
	v_cmp_ge_i32_e32 vcc, s36, v10
	v_cmp_lt_i32_e64 s[0:1], s36, v5
	s_and_b64 vcc, vcc, s[0:1]
	v_cndmask_b32_e32 v4, v4, v6, vcc
	v_add_u32_e32 v6, 0x7f, v7
	v_ashrrev_i32_e32 v6, 7, v6
	v_sub_u32_e32 v10, s36, v10
	v_add_u32_e32 v6, v6, v5
	v_cndmask_b32_e64 v9, v9, 26, vcc
	v_cndmask_b32_e32 v8, v8, v10, vcc
	v_cmp_ge_i32_e32 vcc, s36, v5
	v_cmp_lt_i32_e64 s[0:1], s36, v6
	s_and_b64 vcc, vcc, s[0:1]
	v_cndmask_b32_e32 v4, v4, v7, vcc
	v_add_u32_e32 v7, 0x7f, v0
	v_ashrrev_i32_e32 v7, 7, v7
	v_sub_u32_e32 v5, s36, v5
	v_add_u32_e32 v7, v7, v6
	v_cndmask_b32_e64 v9, v9, 27, vcc
	v_cndmask_b32_e32 v5, v8, v5, vcc
	v_cmp_ge_i32_e32 vcc, s36, v6
	v_cmp_lt_i32_e64 s[0:1], s36, v7
	s_and_b64 vcc, vcc, s[0:1]
	v_cndmask_b32_e32 v0, v4, v0, vcc
	v_add_u32_e32 v4, 0x7f, v1
	v_ashrrev_i32_e32 v4, 7, v4
	v_sub_u32_e32 v6, s36, v6
	v_add_u32_e32 v4, v4, v7
	v_cndmask_b32_e64 v8, v9, 28, vcc
	v_cndmask_b32_e32 v5, v5, v6, vcc
	v_cmp_ge_i32_e32 vcc, s36, v7
	v_cmp_lt_i32_e64 s[0:1], s36, v4
	s_and_b64 vcc, vcc, s[0:1]
	v_cndmask_b32_e32 v0, v0, v1, vcc
	v_add_u32_e32 v1, 0x7f, v2
	v_ashrrev_i32_e32 v1, 7, v1
	v_sub_u32_e32 v6, s36, v7
	v_add_u32_e32 v1, v1, v4
	v_cndmask_b32_e64 v7, v8, 29, vcc
	v_cndmask_b32_e32 v5, v5, v6, vcc
	v_cmp_ge_i32_e32 vcc, s36, v4
	v_cmp_lt_i32_e64 s[0:1], s36, v1
	s_and_b64 vcc, vcc, s[0:1]
	v_cndmask_b32_e32 v0, v0, v2, vcc
	v_add_u32_e32 v2, 0x7f, v3
	v_ashrrev_i32_e32 v2, 7, v2
	v_sub_u32_e32 v4, s36, v4
	v_add_u32_e32 v2, v2, v1
	v_cndmask_b32_e64 v6, v7, 30, vcc
	v_cndmask_b32_e32 v4, v5, v4, vcc
	v_cmp_ge_i32_e32 vcc, s36, v1
	v_cmp_lt_i32_e64 s[0:1], s36, v2
	v_sub_u32_e32 v1, s36, v1
	s_and_b64 vcc, vcc, s[0:1]
	v_cndmask_b32_e32 v1, v4, v1, vcc
	v_lshlrev_b32_e32 v10, 7, v1
	v_cndmask_b32_e64 v64, v6, 31, vcc
	v_cndmask_b32_e32 v9, v0, v3, vcc
	v_add_u32_e32 v4, v10, v99
	v_lshlrev_b32_e32 v8, 14, v64
	v_cmp_lt_i32_e32 vcc, v4, v9
	v_mov_b64_e32 v[2:3], 0
	v_mov_b64_e32 v[0:1], 0
	v_readlane_b32 s6, v242, 54
	v_readlane_b32 s7, v242, 55
	v_add_u32_e32 v251, -1, v9
	v_add_u32_e32 v243, v10, v99
	v_add_u32_e32 v244, v10, v102
	v_add_u32_e32 v245, v10, v104
	v_add_u32_e32 v246, v10, v106
	v_min_i32_e32 v243, v243, v251
	v_add_u32_e32 v243, v243, v8
	v_lshlrev_b32_e32 v243, 2, v243
	v_min_i32_e32 v244, v244, v251
	v_add_u32_e32 v244, v244, v8
	v_lshlrev_b32_e32 v244, 2, v244
	v_min_i32_e32 v245, v245, v251
	v_add_u32_e32 v245, v245, v8
	v_lshlrev_b32_e32 v245, 2, v245
	v_min_i32_e32 v246, v246, v251
	v_add_u32_e32 v246, v246, v8
	v_lshlrev_b32_e32 v246, 2, v246
	global_load_dword v243, v243, s[6:7]
	global_load_dword v244, v244, s[6:7]
	global_load_dword v245, v245, s[6:7]
	global_load_dword v246, v246, s[6:7]
	s_waitcnt vmcnt(0)
	s_and_saveexec_b64 s[0:1], vcc
	s_cbranch_execz .LBB0_910
	v_add_u32_e32 v0, v4, v8
	v_readlane_b32 s6, v242, 54
	v_ashrrev_i32_e32 v1, 31, v0
	v_readlane_b32 s7, v242, 55
	s_nop 1
	v_lshl_add_u64 v[0:1], v[0:1], 2, s[6:7]
	v_mov_b32_e32 v0, v243
	v_ashrrev_i32_e32 v0, 1, v0
	v_ashrrev_i32_e32 v1, 31, v0
	v_lshlrev_b64 v[0:1], 11, v[0:1]
.LBB0_910:
	s_or_b64 exec, exec, s[0:1]
	v_add_u32_e32 v4, v10, v102
	v_cmp_lt_i32_e32 vcc, v4, v9
	s_and_saveexec_b64 s[0:1], vcc
	s_cbranch_execz .LBB0_912
	v_add_u32_e32 v2, v4, v8
	v_readlane_b32 s6, v242, 54
	v_ashrrev_i32_e32 v3, 31, v2
	v_readlane_b32 s7, v242, 55
	s_nop 1
	v_lshl_add_u64 v[2:3], v[2:3], 2, s[6:7]
	v_mov_b32_e32 v2, v244
	v_ashrrev_i32_e32 v2, 1, v2
	v_ashrrev_i32_e32 v3, 31, v2
	v_lshlrev_b64 v[2:3], 11, v[2:3]
.LBB0_912:
	s_or_b64 exec, exec, s[0:1]
	v_add_u32_e32 v11, v10, v104
	v_cmp_lt_i32_e32 vcc, v11, v9
	v_mov_b64_e32 v[4:5], 0
	v_mov_b64_e32 v[6:7], 0
	s_and_saveexec_b64 s[0:1], vcc
	s_cbranch_execz .LBB0_914
	v_add_u32_e32 v6, v11, v8
	v_readlane_b32 s6, v242, 54
	v_ashrrev_i32_e32 v7, 31, v6
	v_readlane_b32 s7, v242, 55
	s_nop 1
	v_lshl_add_u64 v[6:7], v[6:7], 2, s[6:7]
	v_mov_b32_e32 v6, v245
	v_ashrrev_i32_e32 v6, 1, v6
	v_ashrrev_i32_e32 v7, 31, v6
	v_lshlrev_b64 v[6:7], 11, v[6:7]
.LBB0_914:
	s_or_b64 exec, exec, s[0:1]
	v_add_u32_e32 v10, v10, v106
	v_cmp_lt_i32_e32 vcc, v10, v9
	s_and_saveexec_b64 s[0:1], vcc
	s_cbranch_execz .LBB0_916
	v_add_u32_e32 v4, v10, v8
	v_readlane_b32 s6, v242, 54
	v_ashrrev_i32_e32 v5, 31, v4
	v_readlane_b32 s7, v242, 55
	s_nop 1
	v_lshl_add_u64 v[4:5], v[4:5], 2, s[6:7]
	v_mov_b32_e32 v4, v246
	v_ashrrev_i32_e32 v4, 1, v4
	v_ashrrev_i32_e32 v5, 31, v4
	v_lshlrev_b64 v[4:5], 11, v[4:5]
